# v8: + DPP wave reductions in LN, ctx attention tiles rebalanced to other workgroups
# speedup vs baseline: 1.0302x; 1.0013x over previous
.LBB0_236:
	v_readlane_b32 s2, v252, 33
	v_readlane_b32 s3, v252, 34
	s_andn2_b64 vcc, exec, s[2:3]
	s_movk_i32 s6, 0x100
	s_cbranch_vccnz .LBB0_285
	s_cmpk_eq_i32 s99, 0x100
	s_cselect_b32 s26, 0xc0, 0
	s_cselect_b32 s2, 0xff, -1
	s_cselect_b32 s3, 0x80, 0
	s_add_i32 s26, s84, s26
	s_and_b32 s26, s26, s2
	s_sub_i32 s100, s84, s3
	s_cmpk_lt_u32 s100, 0x80
	s_cselect_b64 s[8:9], 0, -1
	s_cmpk_lt_u32 s26, 0x80
	s_cselect_b64 s[2:3], -1, 0
	s_mov_b64 s[12:13], s[70:71]
	s_andn2_b64 vcc, exec, s[2:3]
	s_cbranch_vccnz .LBB0_261
	s_ashr_i32 s75, s74, 31
	s_load_dwordx2 s[14:15], s[12:13], 0x170
	s_lshl_b64 s[16:17], s[74:75], 2
	s_waitcnt lgkmcnt(0)
	s_add_u32 s18, s12, s16
	s_addc_u32 s19, s13, s17
	s_lshl_b32 s2, s74, 7
	s_ashr_i32 s3, s2, 31
	s_lshl_b64 s[20:21], s[2:3], 2
	s_branch .LBB0_240

.LBB0_261:
	s_mov_b64 s[4:5], s[70:71]
	s_and_b64 vcc, exec, s[8:9]
	s_cbranch_vccnz .LBB0_284
	s_load_dwordx2 s[10:11], s[4:5], 0x150
	s_load_dwordx2 s[12:13], s[4:5], 0x180
	s_mov_b32 s14, s100
	s_branch .LBB0_264

.LBB0_301:
	s_or_b64 exec, exec, s[10:11]
	s_waitcnt vmcnt(0)
	v_mov_b32_e32 v98, v81
	v_mov_b32_e32 v99, v82
	v_mov_b32_e32 v100, v80
	v_mov_b32_e32 v101, v83
	v_pk_add_f32 v[98:99], v[98:99], v[100:101]
	s_waitcnt vmcnt(2)
	v_mov_b32_e32 v100, v77
	v_mov_b32_e32 v101, v78
	v_mov_b32_e32 v102, v76
	v_mov_b32_e32 v103, v79
	v_pk_add_f32 v[100:101], v[100:101], v[102:103]
	v_add_f32_e32 v0, v98, v99
	v_pk_add_f32 v[100:101], v[100:101], v[100:101] op_sel:[0,1] op_sel_hi:[1,0]
	v_add_f32_e32 v98, 0, v0
	s_waitcnt vmcnt(1)
	v_add_f32_e32 v102, v72, v73
	v_add_f32_e32 v104, v74, v75
	s_waitcnt vmcnt(0)
	v_mov_b32_e32 v99, v68
	v_mov_b32_e32 v101, v69
	v_mov_b32_e32 v103, v70
	v_mov_b32_e32 v105, v71
	v_pk_add_f32 v[98:99], v[98:99], v[100:101]
	v_pk_add_f32 v[100:101], v[102:103], v[104:105]
	s_mov_b32 s10, 0x800000
	v_pk_add_f32 v[98:99], v[98:99], v[100:101]
	s_nop 0
	v_add_f32_e32 v0, v98, v99
	s_nop 1
	v_add_f32_dpp v0, v0, v0 quad_perm:[1,0,3,2] row_mask:0xf bank_mask:0xf
	s_nop 1
	v_add_f32_dpp v0, v0, v0 quad_perm:[2,3,0,1] row_mask:0xf bank_mask:0xf
	s_nop 1
	v_add_f32_dpp v0, v0, v0 row_half_mirror row_mask:0xf bank_mask:0xf
	s_nop 1
	v_add_f32_dpp v0, v0, v0 row_mirror row_mask:0xf bank_mask:0xf
	s_nop 1
	v_readlane_b32 s100, v0, 0
	v_readlane_b32 s101, v0, 16
	v_readlane_b32 vcc_lo, v0, 32
	v_readlane_b32 vcc_hi, v0, 48
	s_nop 1
	v_mov_b32_e32 v97, s100
	v_add_f32_e32 v97, s101, v97
	v_add_f32_e32 v97, vcc_lo, v97
	v_add_f32_e32 v97, vcc_hi, v97
	v_fmamk_f32 v81, v97, 0xba800000, v81
	v_fmamk_f32 v80, v97, 0xba800000, v80
	v_fmamk_f32 v83, v97, 0xba800000, v83
	v_fmac_f32_e32 v82, 0xba800000, v97
	v_pk_mul_f32 v[98:99], v[82:83], v[82:83]
	v_pk_mul_f32 v[100:101], v[80:81], v[80:81]
	v_fmamk_f32 v77, v97, 0xba800000, v77
	v_fmamk_f32 v76, v97, 0xba800000, v76
	v_fmamk_f32 v79, v97, 0xba800000, v79
	v_pk_mov_b32 v[102:103], v[100:101], v[98:99] op_sel:[1,0]
	v_mov_b32_e32 v101, v99
	v_fmac_f32_e32 v78, 0xba800000, v97
	v_pk_add_f32 v[98:99], v[102:103], v[100:101]
	v_pk_mul_f32 v[100:101], v[78:79], v[78:79]
	v_pk_mul_f32 v[102:103], v[76:77], v[76:77]
	v_fmamk_f32 v72, v97, 0xba800000, v72
	v_pk_mov_b32 v[104:105], v[102:103], v[100:101] op_sel:[1,0]
	v_mov_b32_e32 v103, v101
	v_fmamk_f32 v73, v97, 0xba800000, v73
	v_fmac_f32_e32 v74, 0xba800000, v97
	v_mul_f32_e32 v0, v72, v72
	v_pk_add_f32 v[100:101], v[104:105], v[102:103]
	v_fmamk_f32 v75, v97, 0xba800000, v75
	v_pk_fma_f32 v[102:103], v[72:73], v[72:73], v[0:1] op_sel_hi:[1,1,0]
	v_mul_f32_e32 v0, v74, v74
	v_pk_add_f32 v[98:99], v[98:99], v[98:99] op_sel_hi:[0,1]
	v_pk_add_f32 v[100:101], v[100:101], v[100:101] op_sel_hi:[0,1]
	v_pk_fma_f32 v[104:105], v[74:75], v[74:75], v[0:1] op_sel_hi:[1,1,0]
	v_fmamk_f32 v71, v97, 0xba800000, v71
	v_fmamk_f32 v70, v97, 0xba800000, v70
	v_fmamk_f32 v69, v97, 0xba800000, v69
	v_fmac_f32_e32 v68, 0xba800000, v97
	v_mul_f32_e32 v102, v68, v68
	v_mul_f32_e32 v104, v69, v69
	v_mul_f32_e32 v98, v70, v70
	v_mul_f32_e32 v100, v71, v71
	v_pk_add_f32 v[102:103], v[102:103], v[104:105]
	v_pk_add_f32 v[98:99], v[98:99], v[100:101]
	s_nop 0
	v_pk_add_f32 v[98:99], v[102:103], v[98:99]
	s_nop 0
	v_add_f32_e32 v0, v98, v99
	s_nop 1
	v_add_f32_dpp v0, v0, v0 quad_perm:[1,0,3,2] row_mask:0xf bank_mask:0xf
	s_nop 1
	v_add_f32_dpp v0, v0, v0 quad_perm:[2,3,0,1] row_mask:0xf bank_mask:0xf
	s_nop 1
	v_add_f32_dpp v0, v0, v0 row_half_mirror row_mask:0xf bank_mask:0xf
	s_nop 1
	v_add_f32_dpp v0, v0, v0 row_mirror row_mask:0xf bank_mask:0xf
	s_nop 1
	v_readlane_b32 s100, v0, 0
	v_readlane_b32 s101, v0, 16
	v_readlane_b32 vcc_lo, v0, 32
	v_readlane_b32 vcc_hi, v0, 48
	s_nop 1
	v_mov_b32_e32 v0, s100
	v_add_f32_e32 v0, s101, v0
	v_add_f32_e32 v0, vcc_lo, v0
	v_add_f32_e32 v0, vcc_hi, v0
	v_fmamk_f32 v0, v0, 0x3a800000, v227
	v_mul_f32_e32 v97, 0x4b800000, v0
	v_cmp_gt_f32_e32 vcc, s10, v0
	s_nop 1
	v_cndmask_b32_e32 v0, v0, v97, vcc
	v_rsq_f32_e32 v0, v0
	s_nop 0
	v_mul_f32_e32 v97, 0x45800000, v0
	v_cndmask_b32_e32 v0, v0, v97, vcc
	v_pk_mul_f32 v[80:81], v[80:81], v[0:1] op_sel_hi:[1,0]
	v_pk_mul_f32 v[82:83], v[82:83], v[0:1] op_sel_hi:[1,0]
	v_pk_mul_f32 v[76:77], v[76:77], v[0:1] op_sel_hi:[1,0]
	v_pk_mul_f32 v[78:79], v[78:79], v[0:1] op_sel_hi:[1,0]
	v_pk_mul_f32 v[72:73], v[72:73], v[0:1] op_sel_hi:[1,0]
	v_pk_mul_f32 v[74:75], v[74:75], v[0:1] op_sel_hi:[1,0]
	v_pk_mul_f32 v[68:69], v[68:69], v[0:1] op_sel_hi:[1,0]
	v_pk_mul_f32 v[70:71], v[70:71], v[0:1] op_sel_hi:[1,0]
	v_pk_fma_f32 v[82:83], v[6:7], v[82:83], v[14:15]
	v_pk_fma_f32 v[80:81], v[4:5], v[80:81], v[12:13]
	v_pk_fma_f32 v[78:79], v[10:11], v[78:79], v[18:19]
	v_pk_fma_f32 v[76:77], v[8:9], v[76:77], v[16:17]
	v_pk_fma_f32 v[74:75], v[22:23], v[74:75], v[30:31]
	v_pk_fma_f32 v[72:73], v[20:21], v[72:73], v[28:29]
	v_pk_fma_f32 v[70:71], v[26:27], v[70:71], v[34:35]
	v_pk_fma_f32 v[68:69], v[24:25], v[68:69], v[32:33]
	s_andn2_b64 vcc, exec, s[4:5]
	global_store_dwordx4 v[88:89], v[80:83], off
	global_store_dwordx4 v[88:89], v[76:79], off offset:1024
	global_store_dwordx4 v[88:89], v[72:75], off offset:2048
	global_store_dwordx4 v[88:89], v[68:71], off offset:3072
	s_cbranch_vccnz .LBB0_298
	v_mov_b32_e32 v88, v81
	v_mov_b32_e32 v89, v82
	v_mov_b32_e32 v98, v80
	v_mov_b32_e32 v99, v83
	v_pk_add_f32 v[88:89], v[88:89], v[98:99]
	v_mov_b32_e32 v98, v77
	v_mov_b32_e32 v99, v78
	v_mov_b32_e32 v100, v76
	v_mov_b32_e32 v101, v79
	v_pk_add_f32 v[98:99], v[98:99], v[100:101]
	v_add_f32_e32 v0, v88, v89
	v_pk_add_f32 v[98:99], v[98:99], v[98:99] op_sel_hi:[0,1]
	v_add_f32_e32 v89, 0, v0
	v_add_f32_e32 v101, v72, v73
	v_add_f32_e32 v103, v74, v75
	v_mov_b32_e32 v100, v68
	v_mov_b32_e32 v102, v69
	v_mov_b32_e32 v98, v70
	v_mov_b32_e32 v88, v71
	v_pk_add_f32 v[100:101], v[100:101], v[102:103]
	v_pk_add_f32 v[88:89], v[98:99], v[88:89]
	v_lshlrev_b64 v[2:3], 10, v[2:3]
	v_pk_add_f32 v[88:89], v[100:101], v[88:89]
	s_nop 0
	v_add_f32_e32 v0, v88, v89
	s_nop 1
	v_add_f32_dpp v0, v0, v0 quad_perm:[1,0,3,2] row_mask:0xf bank_mask:0xf
	s_nop 1
	v_add_f32_dpp v0, v0, v0 quad_perm:[2,3,0,1] row_mask:0xf bank_mask:0xf
	s_nop 1
	v_add_f32_dpp v0, v0, v0 row_half_mirror row_mask:0xf bank_mask:0xf
	s_nop 1
	v_add_f32_dpp v0, v0, v0 row_mirror row_mask:0xf bank_mask:0xf
	s_nop 1
	v_readlane_b32 s100, v0, 0
	v_readlane_b32 s101, v0, 16
	v_readlane_b32 vcc_lo, v0, 32
	v_readlane_b32 vcc_hi, v0, 48
	s_nop 1
	v_mov_b32_e32 v97, s100
	v_add_f32_e32 v97, s101, v97
	v_add_f32_e32 v97, vcc_lo, v97
	v_add_f32_e32 v97, vcc_hi, v97
	v_fmamk_f32 v81, v97, 0xba800000, v81
	v_fmamk_f32 v80, v97, 0xba800000, v80
	v_fmamk_f32 v83, v97, 0xba800000, v83
	v_fmac_f32_e32 v82, 0xba800000, v97
	v_pk_mul_f32 v[88:89], v[82:83], v[82:83]
	v_pk_mul_f32 v[98:99], v[80:81], v[80:81]
	v_fmamk_f32 v77, v97, 0xba800000, v77
	v_pk_mov_b32 v[100:101], v[98:99], v[88:89] op_sel:[1,0]
	v_mov_b32_e32 v99, v89
	v_fmamk_f32 v76, v97, 0xba800000, v76
	v_fmamk_f32 v79, v97, 0xba800000, v79
	v_fmac_f32_e32 v78, 0xba800000, v97
	v_pk_add_f32 v[88:89], v[100:101], v[98:99]
	v_pk_mul_f32 v[98:99], v[78:79], v[78:79]
	v_pk_mul_f32 v[100:101], v[76:77], v[76:77]
	v_fmamk_f32 v72, v97, 0xba800000, v72
	v_pk_mov_b32 v[102:103], v[100:101], v[98:99] op_sel:[1,0]
	v_mov_b32_e32 v101, v99
	v_fmamk_f32 v73, v97, 0xba800000, v73
	v_fmac_f32_e32 v74, 0xba800000, v97
	v_mul_f32_e32 v0, v72, v72
	v_pk_add_f32 v[98:99], v[102:103], v[100:101]
	v_fmamk_f32 v75, v97, 0xba800000, v75
	v_pk_fma_f32 v[100:101], v[72:73], v[72:73], v[0:1] op_sel_hi:[1,1,0]
	v_mul_f32_e32 v0, v74, v74
	v_pk_add_f32 v[88:89], v[88:89], v[88:89] op_sel_hi:[0,1]
	v_pk_add_f32 v[98:99], v[98:99], v[98:99] op_sel_hi:[0,1]
	v_pk_fma_f32 v[102:103], v[74:75], v[74:75], v[0:1] op_sel_hi:[1,1,0]
	v_fmamk_f32 v71, v97, 0xba800000, v71
	v_fmamk_f32 v70, v97, 0xba800000, v70
	v_fmamk_f32 v69, v97, 0xba800000, v69
	v_fmac_f32_e32 v68, 0xba800000, v97
	v_mul_f32_e32 v100, v68, v68
	v_mul_f32_e32 v102, v69, v69
	v_mul_f32_e32 v88, v70, v70
	v_mul_f32_e32 v98, v71, v71
	v_pk_add_f32 v[100:101], v[100:101], v[102:103]
	v_pk_add_f32 v[88:89], v[88:89], v[98:99]
	v_pk_add_f32 v[98:99], v[50:51], 1.0 op_sel_hi:[1,0]
	v_pk_add_f32 v[88:89], v[100:101], v[88:89]
	v_pk_add_f32 v[100:101], v[48:49], 1.0 op_sel_hi:[1,0]
	v_add_f32_e32 v0, v88, v89
	s_nop 1
	v_add_f32_dpp v0, v0, v0 quad_perm:[1,0,3,2] row_mask:0xf bank_mask:0xf
	s_nop 1
	v_add_f32_dpp v0, v0, v0 quad_perm:[2,3,0,1] row_mask:0xf bank_mask:0xf
	s_nop 1
	v_add_f32_dpp v0, v0, v0 row_half_mirror row_mask:0xf bank_mask:0xf
	s_nop 1
	v_add_f32_dpp v0, v0, v0 row_mirror row_mask:0xf bank_mask:0xf
	s_nop 1
	v_readlane_b32 s100, v0, 0
	v_readlane_b32 s101, v0, 16
	v_readlane_b32 vcc_lo, v0, 32
	v_readlane_b32 vcc_hi, v0, 48
	s_nop 1
	v_mov_b32_e32 v0, s100
	v_add_f32_e32 v0, s101, v0
	v_add_f32_e32 v0, vcc_lo, v0
	v_add_f32_e32 v0, vcc_hi, v0
	v_fmamk_f32 v0, v0, 0x3a800000, v227
	v_cmp_gt_f32_e32 vcc, s10, v0
	v_mul_f32_e32 v88, 0x4b800000, v0
	s_load_dwordx2 s[10:11], s[0:1], 0x148
	v_cndmask_b32_e32 v0, v0, v88, vcc
	v_rsq_f32_e32 v0, v0
	s_waitcnt lgkmcnt(0)
	v_lshl_add_u64 v[2:3], v[2:3], 1, s[10:11]
	v_mul_f32_e32 v88, 0x45800000, v0
	v_cndmask_b32_e32 v88, v0, v88, vcc
	v_pk_mul_f32 v[80:81], v[80:81], v[88:89] op_sel_hi:[1,0]
	v_pk_mul_f32 v[82:83], v[82:83], v[88:89] op_sel_hi:[1,0]
	v_lshlrev_b32_e32 v0, 1, v84
	v_pk_fma_f32 v[82:83], v[98:99], v[82:83], v[38:39]
	v_pk_fma_f32 v[80:81], v[100:101], v[80:81], v[36:37]
	v_lshl_add_u64 v[2:3], v[2:3], 0, v[0:1]
	v_cvt_pk_bf16_f32 v80, v80, v81
	v_cvt_pk_bf16_f32 v81, v82, v83
	global_store_dwordx2 v[2:3], v[80:81], off
	v_pk_mul_f32 v[76:77], v[76:77], v[88:89] op_sel_hi:[1,0]
	v_pk_mul_f32 v[78:79], v[78:79], v[88:89] op_sel_hi:[1,0]
	v_pk_add_f32 v[80:81], v[42:43], 1.0 op_sel_hi:[1,0]
	v_pk_add_f32 v[82:83], v[40:41], 1.0 op_sel_hi:[1,0]
	v_pk_fma_f32 v[78:79], v[80:81], v[78:79], v[54:55]
	v_pk_fma_f32 v[76:77], v[82:83], v[76:77], v[52:53]
	v_pk_mul_f32 v[72:73], v[72:73], v[88:89] op_sel_hi:[1,0]
	v_cvt_pk_bf16_f32 v76, v76, v77
	v_cvt_pk_bf16_f32 v77, v78, v79
	global_store_dwordx2 v[2:3], v[76:77], off offset:512
	v_pk_mul_f32 v[74:75], v[74:75], v[88:89] op_sel_hi:[1,0]
	v_pk_add_f32 v[76:77], v[46:47], 1.0 op_sel_hi:[1,0]
	v_pk_add_f32 v[78:79], v[44:45], 1.0 op_sel_hi:[1,0]
	v_pk_fma_f32 v[74:75], v[76:77], v[74:75], v[58:59]
	v_pk_fma_f32 v[72:73], v[78:79], v[72:73], v[56:57]
	v_pk_mul_f32 v[68:69], v[68:69], v[88:89] op_sel_hi:[1,0]
	v_cvt_pk_bf16_f32 v72, v72, v73
	v_cvt_pk_bf16_f32 v73, v74, v75
	global_store_dwordx2 v[2:3], v[72:73], off offset:1024
	v_pk_mul_f32 v[70:71], v[70:71], v[88:89] op_sel_hi:[1,0]
	v_pk_add_f32 v[72:73], v[66:67], 1.0 op_sel_hi:[1,0]
	v_pk_add_f32 v[74:75], v[64:65], 1.0 op_sel_hi:[1,0]
	v_pk_fma_f32 v[70:71], v[72:73], v[70:71], v[62:63]
	v_pk_fma_f32 v[68:69], v[74:75], v[68:69], v[60:61]
	s_nop 0
	v_cvt_pk_bf16_f32 v68, v68, v69
	v_cvt_pk_bf16_f32 v69, v70, v71
	global_store_dwordx2 v[2:3], v[68:69], off offset:1536
	s_branch .LBB0_298

.LBB0_445:
	s_or_b64 exec, exec, s[4:5]
	s_waitcnt vmcnt(0)
	v_mov_b32_e32 v64, v49
	v_mov_b32_e32 v65, v50
	v_mov_b32_e32 v66, v48
	v_mov_b32_e32 v67, v51
	v_pk_add_f32 v[64:65], v[64:65], v[66:67]
	v_mov_b32_e32 v66, v45
	v_mov_b32_e32 v67, v46
	v_mov_b32_e32 v68, v44
	v_mov_b32_e32 v69, v47
	v_pk_add_f32 v[66:67], v[66:67], v[68:69]
	v_add_f32_e32 v0, v64, v65
	v_pk_add_f32 v[66:67], v[66:67], v[66:67] op_sel:[0,1] op_sel_hi:[1,0]
	v_add_f32_e32 v64, 0, v0
	v_add_f32_e32 v68, v40, v41
	v_add_f32_e32 v70, v42, v43
	v_mov_b32_e32 v65, v36
	v_mov_b32_e32 v67, v37
	v_mov_b32_e32 v69, v38
	v_mov_b32_e32 v71, v39
	v_pk_add_f32 v[64:65], v[64:65], v[66:67]
	v_pk_add_f32 v[66:67], v[68:69], v[70:71]
	s_mov_b32 s3, 0x800000
	v_pk_add_f32 v[64:65], v[64:65], v[66:67]
	v_lshl_add_u64 v[2:3], v[2:3], 1, v[54:55]
	v_add_f32_e32 v0, v64, v65
	s_add_i32 s2, s2, s99
	s_cmpk_gt_i32 s2, 0x11ff
	v_add_u32_e32 v56, s12, v56
	s_nop 1
	v_add_f32_dpp v0, v0, v0 quad_perm:[1,0,3,2] row_mask:0xf bank_mask:0xf
	s_nop 1
	v_add_f32_dpp v0, v0, v0 quad_perm:[2,3,0,1] row_mask:0xf bank_mask:0xf
	s_nop 1
	v_add_f32_dpp v0, v0, v0 row_half_mirror row_mask:0xf bank_mask:0xf
	s_nop 1
	v_add_f32_dpp v0, v0, v0 row_mirror row_mask:0xf bank_mask:0xf
	s_nop 1
	v_readlane_b32 s100, v0, 0
	v_readlane_b32 s101, v0, 16
	v_readlane_b32 vcc_lo, v0, 32
	v_readlane_b32 vcc_hi, v0, 48
	s_nop 1
	v_mov_b32_e32 v57, s100
	v_add_f32_e32 v57, s101, v57
	v_add_f32_e32 v57, vcc_lo, v57
	v_add_f32_e32 v57, vcc_hi, v57
	v_fmamk_f32 v49, v57, 0xba800000, v49
	v_fmamk_f32 v48, v57, 0xba800000, v48
	v_fmamk_f32 v51, v57, 0xba800000, v51
	v_fmac_f32_e32 v50, 0xba800000, v57
	v_pk_mul_f32 v[64:65], v[50:51], v[50:51]
	v_pk_mul_f32 v[66:67], v[48:49], v[48:49]
	v_fmamk_f32 v45, v57, 0xba800000, v45
	v_fmamk_f32 v44, v57, 0xba800000, v44
	v_fmamk_f32 v47, v57, 0xba800000, v47
	v_pk_mov_b32 v[68:69], v[66:67], v[64:65] op_sel:[1,0]
	v_mov_b32_e32 v67, v65
	v_fmac_f32_e32 v46, 0xba800000, v57
	v_pk_add_f32 v[64:65], v[68:69], v[66:67]
	v_pk_mul_f32 v[66:67], v[46:47], v[46:47]
	v_pk_mul_f32 v[68:69], v[44:45], v[44:45]
	v_fmamk_f32 v40, v57, 0xba800000, v40
	v_pk_mov_b32 v[70:71], v[68:69], v[66:67] op_sel:[1,0]
	v_mov_b32_e32 v69, v67
	v_fmamk_f32 v41, v57, 0xba800000, v41
	v_fmac_f32_e32 v42, 0xba800000, v57
	v_mul_f32_e32 v0, v40, v40
	v_pk_add_f32 v[66:67], v[70:71], v[68:69]
	v_fmamk_f32 v43, v57, 0xba800000, v43
	v_pk_fma_f32 v[68:69], v[40:41], v[40:41], v[0:1] op_sel_hi:[1,1,0]
	v_mul_f32_e32 v0, v42, v42
	v_pk_add_f32 v[64:65], v[64:65], v[64:65] op_sel_hi:[0,1]
	v_pk_add_f32 v[66:67], v[66:67], v[66:67] op_sel_hi:[0,1]
	v_pk_fma_f32 v[70:71], v[42:43], v[42:43], v[0:1] op_sel_hi:[1,1,0]
	v_fmamk_f32 v39, v57, 0xba800000, v39
	v_fmamk_f32 v38, v57, 0xba800000, v38
	v_fmamk_f32 v37, v57, 0xba800000, v37
	v_fmac_f32_e32 v36, 0xba800000, v57
	v_mul_f32_e32 v68, v36, v36
	v_mul_f32_e32 v70, v37, v37
	v_mul_f32_e32 v64, v38, v38
	v_mul_f32_e32 v66, v39, v39
	v_pk_add_f32 v[68:69], v[68:69], v[70:71]
	v_pk_add_f32 v[64:65], v[64:65], v[66:67]
	v_pk_add_f32 v[66:67], v[16:17], 1.0 op_sel_hi:[1,0]
	v_pk_add_f32 v[64:65], v[68:69], v[64:65]
	s_nop 0
	v_add_f32_e32 v0, v64, v65
	v_pk_add_f32 v[64:65], v[18:19], 1.0 op_sel_hi:[1,0]
	s_nop 1
	v_add_f32_dpp v0, v0, v0 quad_perm:[1,0,3,2] row_mask:0xf bank_mask:0xf
	s_nop 1
	v_add_f32_dpp v0, v0, v0 quad_perm:[2,3,0,1] row_mask:0xf bank_mask:0xf
	s_nop 1
	v_add_f32_dpp v0, v0, v0 row_half_mirror row_mask:0xf bank_mask:0xf
	s_nop 1
	v_add_f32_dpp v0, v0, v0 row_mirror row_mask:0xf bank_mask:0xf
	s_nop 1
	v_readlane_b32 s100, v0, 0
	v_readlane_b32 s101, v0, 16
	v_readlane_b32 vcc_lo, v0, 32
	v_readlane_b32 vcc_hi, v0, 48
	s_nop 1
	v_mov_b32_e32 v0, s100
	v_add_f32_e32 v0, s101, v0
	v_add_f32_e32 v0, vcc_lo, v0
	v_add_f32_e32 v0, vcc_hi, v0
	v_fmamk_f32 v0, v0, 0x3a800000, v227
	v_mul_f32_e32 v57, 0x4b800000, v0
	v_cmp_gt_f32_e32 vcc, s3, v0
	s_nop 1
	v_cndmask_b32_e32 v0, v0, v57, vcc
	v_rsq_f32_e32 v0, v0
	s_nop 0
	v_mul_f32_e32 v57, 0x45800000, v0
	v_cndmask_b32_e32 v0, v0, v57, vcc
	v_pk_mul_f32 v[48:49], v[48:49], v[0:1] op_sel_hi:[1,0]
	v_pk_mul_f32 v[50:51], v[50:51], v[0:1] op_sel_hi:[1,0]
	v_pk_fma_f32 v[48:49], v[66:67], v[48:49], v[4:5]
	v_pk_fma_f32 v[50:51], v[64:65], v[50:51], v[6:7]
	v_cvt_pk_bf16_f32 v48, v48, v49
	v_cvt_pk_bf16_f32 v49, v50, v51
	global_store_dwordx2 v[2:3], v[48:49], off
	v_pk_mul_f32 v[44:45], v[44:45], v[0:1] op_sel_hi:[1,0]
	v_pk_mul_f32 v[46:47], v[46:47], v[0:1] op_sel_hi:[1,0]
	v_pk_add_f32 v[48:49], v[10:11], 1.0 op_sel_hi:[1,0]
	v_pk_add_f32 v[50:51], v[8:9], 1.0 op_sel_hi:[1,0]
	v_pk_fma_f32 v[46:47], v[48:49], v[46:47], v[22:23]
	v_pk_fma_f32 v[44:45], v[50:51], v[44:45], v[20:21]
	v_pk_mul_f32 v[40:41], v[40:41], v[0:1] op_sel_hi:[1,0]
	v_cvt_pk_bf16_f32 v44, v44, v45
	v_cvt_pk_bf16_f32 v45, v46, v47
	global_store_dwordx2 v[2:3], v[44:45], off offset:512
	v_pk_mul_f32 v[42:43], v[42:43], v[0:1] op_sel_hi:[1,0]
	v_pk_add_f32 v[44:45], v[14:15], 1.0 op_sel_hi:[1,0]
	v_pk_add_f32 v[46:47], v[12:13], 1.0 op_sel_hi:[1,0]
	v_pk_fma_f32 v[42:43], v[44:45], v[42:43], v[26:27]
	v_pk_fma_f32 v[40:41], v[46:47], v[40:41], v[24:25]
	v_pk_mul_f32 v[36:37], v[36:37], v[0:1] op_sel_hi:[1,0]
	v_cvt_pk_bf16_f32 v40, v40, v41
	v_cvt_pk_bf16_f32 v41, v42, v43
	global_store_dwordx2 v[2:3], v[40:41], off offset:1024
	v_pk_mul_f32 v[38:39], v[38:39], v[0:1] op_sel_hi:[1,0]
	v_pk_add_f32 v[40:41], v[34:35], 1.0 op_sel_hi:[1,0]
	v_pk_add_f32 v[42:43], v[32:33], 1.0 op_sel_hi:[1,0]
	v_pk_fma_f32 v[38:39], v[40:41], v[38:39], v[30:31]
	v_pk_fma_f32 v[36:37], v[42:43], v[36:37], v[28:29]
	s_nop 0
	v_cvt_pk_bf16_f32 v36, v36, v37
	v_cvt_pk_bf16_f32 v37, v38, v39
	global_store_dwordx2 v[2:3], v[36:37], off offset:1536
	s_cbranch_scc1 .LBB0_452

	.amdhsa_kernel _Z10fwd_kernel6Params
		.amdhsa_group_segment_fixed_size 147456
		.amdhsa_private_segment_fixed_size 0
		.amdhsa_kernarg_size 704
		.amdhsa_user_sgpr_count 2
		.amdhsa_user_sgpr_dispatch_ptr 0
		.amdhsa_user_sgpr_queue_ptr 0
		.amdhsa_user_sgpr_kernarg_segment_ptr 1
		.amdhsa_user_sgpr_dispatch_id 0
		.amdhsa_user_sgpr_kernarg_preload_length 0
		.amdhsa_user_sgpr_kernarg_preload_offset 0
		.amdhsa_user_sgpr_private_segment_size 0
		.amdhsa_uses_dynamic_stack 0
		.amdhsa_enable_private_segment 0
		.amdhsa_system_sgpr_workgroup_id_x 1
		.amdhsa_system_sgpr_workgroup_id_y 0
		.amdhsa_system_sgpr_workgroup_id_z 0
		.amdhsa_system_sgpr_workgroup_info 0
		.amdhsa_system_vgpr_workitem_id 2
		.amdhsa_next_free_vgpr 256
		.amdhsa_next_free_sgpr 102
		.amdhsa_accum_offset 256
		.amdhsa_reserve_vcc 1
		.amdhsa_float_round_mode_32 0
		.amdhsa_float_round_mode_16_64 0
		.amdhsa_float_denorm_mode_32 3
		.amdhsa_float_denorm_mode_16_64 3
		.amdhsa_dx10_clamp 1
		.amdhsa_ieee_mode 1
		.amdhsa_fp16_overflow 0
		.amdhsa_tg_split 0
		.amdhsa_exception_fp_ieee_invalid_op 0
		.amdhsa_exception_fp_denorm_src 0
		.amdhsa_exception_fp_ieee_div_zero 0
		.amdhsa_exception_fp_ieee_overflow 0
		.amdhsa_exception_fp_ieee_underflow 0
		.amdhsa_exception_fp_ieee_inexact 0
		.amdhsa_exception_int_div_zero 0
	.end_amdhsa_kernel

amdhsa.kernels:
  - .agpr_count:     0
    .args:
      - .offset:         0
        .size:           448
        .value_kind:     by_value
      - .offset:         448
        .size:           4
        .value_kind:     hidden_block_count_x
      - .offset:         452
        .size:           4
        .value_kind:     hidden_block_count_y
      - .offset:         456
        .size:           4
        .value_kind:     hidden_block_count_z
      - .offset:         460
        .size:           2
        .value_kind:     hidden_group_size_x
      - .offset:         462
        .size:           2
        .value_kind:     hidden_group_size_y
      - .offset:         464
        .size:           2
        .value_kind:     hidden_group_size_z
      - .offset:         466
        .size:           2
        .value_kind:     hidden_remainder_x
      - .offset:         468
        .size:           2
        .value_kind:     hidden_remainder_y
      - .offset:         470
        .size:           2
        .value_kind:     hidden_remainder_z
      - .offset:         488
        .size:           8
        .value_kind:     hidden_global_offset_x
      - .offset:         496
        .size:           8
        .value_kind:     hidden_global_offset_y
      - .offset:         504
        .size:           8
        .value_kind:     hidden_global_offset_z
      - .offset:         512
        .size:           2
        .value_kind:     hidden_grid_dims
      - .offset:         536
        .size:           8
        .value_kind:     hidden_multigrid_sync_arg
    .group_segment_fixed_size: 147456
    .kernarg_segment_align: 8
    .kernarg_segment_size: 704
    .language:       OpenCL C
    .language_version:
      - 2
      - 0
    .max_flat_workgroup_size: 512
    .name:           _Z10fwd_kernel6Params
    .private_segment_fixed_size: 0
    .sgpr_count:     108
    .sgpr_spill_count: 49
    .symbol:         _Z10fwd_kernel6Params.kd
    .uniform_work_group_size: 1
    .uses_dynamic_stack: false
    .vgpr_count:     256
    .vgpr_spill_count: 0
    .wavefront_size: 64
